# prompt attention: table-bias K tiles also straight-line (4 neighbouring rows fetched from one clamped table address via ds_read2_b32, packed fma/add), compiler's branchy softmax body deleted
# speedup vs baseline: 1.0145x; 1.0127x over previous
.LBB0_877:
	s_mov_b64 s[4:5], 0
	s_and_b64 vcc, exec, s[2:3]
	s_mov_b64 s[36:37], 0
	s_cbranch_vccz .LBB0_1032
	v_mov_b32_e32 v0, v252
	s_waitcnt vmcnt(63) expcnt(7) lgkmcnt(15)
	v_readfirstlane_b32 s6, v0
	s_barrier
	s_load_dwordx2 s[2:3], s[0:1], 0x40
	s_ashr_i32 s33, s6, 6
	s_mul_i32 s8, s33, 0x101
	v_and_b32_e32 v168, 63, v0
	s_mul_i32 s7, s33, 0x410
	s_ashr_i32 s9, s8, 31
	v_mov_b32_e32 v169, v1
	s_add_i32 s30, s7, 0
	v_lshl_add_u64 v[2:3], s[8:9], 0, v[168:169]
	v_or_b32_e32 v4, 0xffffffc0, v168
	v_lshl_add_u32 v5, v168, 2, s30
	s_waitcnt lgkmcnt(0)
	v_lshl_add_u64 v[2:3], v[2:3], 2, s[2:3]
	s_mov_b64 s[2:3], 0
	global_load_dword v243, v[2:3], off
	global_load_dword v248, v[2:3], off offset:256
	global_load_dword v249, v[2:3], off offset:512
	global_load_dword v250, v[2:3], off offset:768
	v_cmp_eq_u32_e32 vcc, 0xffffffc0, v4
	s_and_saveexec_b64 s[2:3], vcc
	global_load_dword v251, v[2:3], off offset:1024
	s_waitcnt vmcnt(0)
	v_mul_f32_e32 v251, 0x3fb8aa3b, v251
	ds_write_b32 v5, v251 offset:1024
	ds_write_b32 v5, v251 offset:1028
	ds_write_b32 v5, v251 offset:1032
	ds_write_b32 v5, v251 offset:1036
	s_or_b64 exec, exec, s[2:3]
	v_mul_f32_e32 v243, 0x3fb8aa3b, v243
	v_mul_f32_e32 v248, 0x3fb8aa3b, v248
	v_mul_f32_e32 v249, 0x3fb8aa3b, v249
	v_mul_f32_e32 v250, 0x3fb8aa3b, v250
	ds_write_b32 v5, v243
	ds_write_b32 v5, v248 offset:256
	ds_write_b32 v5, v249 offset:512
	ds_write_b32 v5, v250 offset:768
	s_add_i32 s2, s18, 0xfffffba9
	s_lshl_b32 s3, s2, 5
	s_mul_hi_u32 s38, s2, 0x88000
	s_mul_i32 s39, s2, 0x88000
	s_andn2_b32 s6, s6, 63
	s_lshl_b32 s2, s2, 3
	s_ashr_i32 s7, s6, 31
	s_add_i32 s2, s33, s2
	s_add_i32 s76, s3, 0x8000
	s_mul_hi_i32 s40, s2, 0x11000
	s_mul_i32 s41, s2, 0x11000
	s_add_u32 s8, s79, s39
	v_readlane_b32 s2, v254, 46
	s_addc_u32 s9, s2, s38
	s_lshl_b64 s[2:3], s[6:7], 1
	s_add_u32 s10, s8, s2
	s_addc_u32 s11, s9, s3
	v_readlane_b32 s8, v254, 48
	s_add_u32 s8, s8, s41
	v_readlane_b32 s9, v254, 50
	s_addc_u32 s9, s9, s40
	v_and_b32_e32 v169, 31, v0
	v_lshrrev_b32_e32 v15, 5, v168
	s_add_u32 s36, s95, s2
	s_addc_u32 s37, s22, s3
	v_lshlrev_b32_e32 v0, 4, v15
	v_or_b32_e32 v166, s76, v169
	v_mov_b32_e32 v167, v1
	v_lshl_add_u64 v[2:3], s[36:37], 0, v[0:1]
	v_lshlrev_b64 v[4:5], 10, v[166:167]
	s_lshl_b64 s[36:37], s[76:77], 10
	v_lshl_add_u64 v[4:5], v[2:3], 0, v[4:5]
	v_lshl_add_u64 v[2:3], v[2:3], 0, s[36:37]
	s_movk_i32 s31, 0x7000
	v_add_co_u32_e32 v2, vcc, s31, v2
	s_waitcnt lgkmcnt(0)
	s_nop 0
	v_addc_co_u32_e32 v3, vcc, 0, v3, vcc
	s_barrier
	global_load_dwordx4 v[16:19], v[4:5], off
	global_load_dwordx4 v[20:23], v[4:5], off offset:32
	global_load_dwordx4 v[24:27], v[4:5], off offset:64
	global_load_dwordx4 v[28:31], v[4:5], off offset:96
	global_load_dwordx4 v[32:35], v[2:3], off offset:3072
	global_load_dwordx4 v[36:39], v[2:3], off offset:3104
	global_load_dwordx4 v[40:43], v[2:3], off offset:3136
	global_load_dwordx4 v[44:47], v[2:3], off offset:3168
	s_mul_i32 s36, s33, 0x1bf0
	v_lshlrev_b32_e32 v48, 4, v168
	v_lshlrev_b32_e32 v49, 4, v169
	v_lshl_add_u64 v[172:173], s[10:11], 0, v[0:1]
	s_add_i32 s10, s30, s36
	v_add_u32_e32 v189, s10, v48
	v_lshl_or_b32 v0, v15, 10, v49
	s_add_u32 s10, s39, 0xa5ee240
	v_lshl_add_u64 v[174:175], s[8:9], 0, v[0:1]
	v_or_b32_e32 v170, s41, v0
	s_addc_u32 s11, s38, 0
	v_lshlrev_b32_e32 v0, 10, v169
	v_lshrrev_b32_e32 v50, 1, v168
	v_lshl_add_u64 v[48:49], s[10:11], 0, v[0:1]
	v_mov_b32_e32 v14, v1
	v_lshlrev_b32_e32 v165, 2, v15
	v_and_or_b32 v48, v50, 16, v48
	v_mov_b32_e32 v15, v1
	v_mov_b32_e32 v2, v1
	v_mov_b32_e32 v3, v1
	v_mov_b32_e32 v4, v1
	v_mov_b32_e32 v5, v1
	v_mov_b32_e32 v6, v1
	v_mov_b32_e32 v7, v1
	v_mov_b32_e32 v8, v1
	v_mov_b32_e32 v9, v1
	v_mov_b32_e32 v10, v1
	v_mov_b32_e32 v11, v1
	v_mov_b32_e32 v12, v1
	v_mov_b32_e32 v13, v1
	v_mov_b32_e32 v0, v1
	v_lshl_add_u64 v[176:177], v[48:49], 0, s[2:3]
	v_mov_b64_e32 v[62:63], v[14:15]
	v_mov_b64_e32 v[78:79], v[14:15]
	s_mov_b32 s31, 3
	s_mov_b32 s33, 0
	v_sub_u32_e32 v188, v169, v165
	v_mov_b32_e32 v171, s40
	v_mov_b32_e32 v190, 0
	v_mov_b32_e32 v191, 0xf149f2ca
	s_mov_b32 s10, 0
	v_mov_b64_e32 v[60:61], v[12:13]
	v_mov_b64_e32 v[58:59], v[10:11]
	v_mov_b64_e32 v[56:57], v[8:9]
	v_mov_b64_e32 v[54:55], v[6:7]
	v_mov_b64_e32 v[52:53], v[4:5]
	v_mov_b64_e32 v[50:51], v[2:3]
	s_waitcnt vmcnt(7)
	s_waitcnt vmcnt(6)
	s_waitcnt vmcnt(5)
	s_waitcnt vmcnt(4)
	s_waitcnt vmcnt(3)
	s_waitcnt vmcnt(2)
	s_waitcnt vmcnt(1)
	s_waitcnt vmcnt(0)
	ds_write_b128 v189, v[16:19] offset:16384
	ds_write_b128 v189, v[20:23] offset:17408
	ds_write_b128 v189, v[24:27] offset:18432
	ds_write_b128 v189, v[28:31] offset:19456
	ds_write_b128 v189, v[32:35] offset:20480
	ds_write_b128 v189, v[36:39] offset:21504
	ds_write_b128 v189, v[40:43] offset:22528
	ds_write_b128 v189, v[44:47] offset:23552
	v_mov_b64_e32 v[30:31], v[14:15]
	v_mov_b64_e32 v[46:47], v[14:15]
	v_mov_b64_e32 v[28:29], v[12:13]
	v_mov_b64_e32 v[26:27], v[10:11]
	v_mov_b64_e32 v[24:25], v[8:9]
	v_mov_b64_e32 v[22:23], v[6:7]
	v_mov_b64_e32 v[20:21], v[4:5]
	v_mov_b64_e32 v[18:19], v[2:3]
	v_mov_b64_e32 v[16:17], v[0:1]
	v_mov_b64_e32 v[48:49], v[0:1]
	v_mov_b64_e32 v[44:45], v[12:13]
	v_mov_b64_e32 v[42:43], v[10:11]
	v_mov_b64_e32 v[40:41], v[8:9]
	v_mov_b64_e32 v[38:39], v[6:7]
	v_mov_b64_e32 v[36:37], v[4:5]
	v_mov_b64_e32 v[34:35], v[2:3]
	v_mov_b64_e32 v[32:33], v[0:1]
	v_mov_b64_e32 v[76:77], v[12:13]
	v_mov_b64_e32 v[74:75], v[10:11]
	v_mov_b64_e32 v[72:73], v[8:9]
	v_mov_b64_e32 v[70:71], v[6:7]
	v_mov_b64_e32 v[68:69], v[4:5]
	v_mov_b64_e32 v[66:67], v[2:3]
	v_mov_b64_e32 v[64:65], v[0:1]
	v_mov_b32_e32 v209, 0xf149f2ca
	v_mov_b32_e32 v15, 0
	s_mov_b32 s11, 0

.LBB0_1129:
	v_mov_b32_e32 v0, v252
	s_waitcnt vmcnt(63) expcnt(7) lgkmcnt(15)
	v_readfirstlane_b32 s4, v0
	s_barrier
	s_load_dwordx2 s[2:3], s[0:1], 0x40
	s_ashr_i32 s8, s4, 6
	s_mul_i32 s6, s8, 0x101
	v_and_b32_e32 v168, 63, v0
	s_mul_i32 s5, s8, 0x410
	s_ashr_i32 s7, s6, 31
	v_mov_b32_e32 v169, v1
	s_add_i32 s10, s5, 0
	v_lshl_add_u64 v[2:3], s[6:7], 0, v[168:169]
	v_or_b32_e32 v4, 0xffffffc0, v168
	v_lshl_add_u32 v5, v168, 2, s10
	s_waitcnt lgkmcnt(0)
	v_lshl_add_u64 v[2:3], v[2:3], 2, s[2:3]
	s_mov_b64 s[2:3], 0
	global_load_dword v243, v[2:3], off
	global_load_dword v248, v[2:3], off offset:256
	global_load_dword v249, v[2:3], off offset:512
	global_load_dword v250, v[2:3], off offset:768
	v_cmp_eq_u32_e32 vcc, 0xffffffc0, v4
	s_and_saveexec_b64 s[2:3], vcc
	global_load_dword v251, v[2:3], off offset:1024
	s_waitcnt vmcnt(0)
	v_mul_f32_e32 v251, 0x3fb8aa3b, v251
	ds_write_b32 v5, v251 offset:1024
	ds_write_b32 v5, v251 offset:1028
	ds_write_b32 v5, v251 offset:1032
	ds_write_b32 v5, v251 offset:1036
	s_or_b64 exec, exec, s[2:3]
	v_mul_f32_e32 v243, 0x3fb8aa3b, v243
	v_mul_f32_e32 v248, 0x3fb8aa3b, v248
	v_mul_f32_e32 v249, 0x3fb8aa3b, v249
	v_mul_f32_e32 v250, 0x3fb8aa3b, v250
	ds_write_b32 v5, v243
	ds_write_b32 v5, v248 offset:256
	ds_write_b32 v5, v249 offset:512
	ds_write_b32 v5, v250 offset:768
	s_add_i32 s2, s18, 0xfffffbd9
	s_lshl_b32 s3, s2, 7
	s_and_b32 s9, s3, 0x180
	s_or_b32 s3, s9, 7
	s_lshr_b32 s11, s2, 2
	s_sub_i32 s33, s3, s11
	s_and_b32 s2, s33, 0x7f
	s_lshl_b32 s2, s2, 16
	v_readlane_b32 s3, v254, 34
	s_add_u32 s2, s3, s2
	v_readlane_b32 s3, v254, 40
	s_addc_u32 s3, s3, 0
	s_andn2_b32 s4, s4, 63
	s_lshl_b32 s6, s33, 16
	s_ashr_i32 s5, s4, 31
	s_and_b32 s6, s6, 0x1800000
	s_add_u32 s6, s2, s6
	s_addc_u32 s7, s3, 0
	s_lshl_b64 s[2:3], s[4:5], 1
	s_add_u32 s6, s6, s2
	s_addc_u32 s7, s7, s3
	v_and_b32_e32 v169, 31, v0
	v_lshrrev_b32_e32 v36, 5, v168
	s_add_u32 s30, s95, s2
	s_addc_u32 s31, s22, s3
	v_lshlrev_b32_e32 v0, 4, v36
	v_lshl_or_b32 v166, s33, 6, v169
	v_lshl_add_u64 v[2:3], s[30:31], 0, v[0:1]
	v_lshlrev_b32_e32 v4, 10, v166
	v_mov_b32_e32 v5, v1
	v_or_b32_e32 v165, 32, v166
	v_lshl_add_u64 v[16:17], v[2:3], 0, v[4:5]
	v_lshlrev_b32_e32 v4, 10, v165
	s_waitcnt lgkmcnt(0)
	s_barrier
	v_lshl_add_u64 v[2:3], v[2:3], 0, v[4:5]
	global_load_dwordx4 v[4:7], v[16:17], off
	global_load_dwordx4 v[8:11], v[16:17], off offset:32
	global_load_dwordx4 v[12:15], v[16:17], off offset:64
	s_nop 0
	global_load_dwordx4 v[16:19], v[16:17], off offset:96
	s_nop 0
	global_load_dwordx4 v[20:23], v[2:3], off
	global_load_dwordx4 v[24:27], v[2:3], off offset:32
	global_load_dwordx4 v[28:31], v[2:3], off offset:64
	global_load_dwordx4 v[32:35], v[2:3], off offset:96
	v_lshlrev_b32_e32 v37, 4, v169
	v_lshlrev_b32_e32 v167, 2, v36
	v_lshl_or_b32 v39, v36, 10, v37
	v_lshl_add_u64 v[36:37], s[6:7], 0, v[0:1]
	s_mov_b32 s6, 0xfff80000
	s_mov_b32 s7, -1
	v_lshl_add_u64 v[172:173], v[36:37], 0, s[6:7]
	s_sub_i32 s6, 7, s11
	s_sub_i32 s7, s9, s11
	s_and_b32 s6, s6, 0x7f
	s_add_i32 s7, s7, 7
	s_min_u32 s9, s6, 8
	s_lshr_b32 s7, s7, 4
	s_lshl_b32 s31, s6, 13
	s_sub_i32 s11, 7, s9
	s_lshl_b32 s33, s9, 6
	s_lshl_b32 s9, s9, 13
	s_and_b32 s6, s7, 0xffffff8
	s_mul_i32 s30, s8, 0x1bf0
	s_sub_i32 s7, 0, s9
	s_add_i32 s6, s8, s6
	v_lshlrev_b32_e32 v38, 4, v168
	s_add_i32 s30, s10, s30
	s_ashr_i32 s8, s7, 31
	v_or_b32_e32 v174, s7, v39
	s_ashr_i32 s7, s6, 31
	v_add_u32_e32 v188, s30, v38
	s_lshl_b64 s[6:7], s[6:7], 20
	s_sub_i32 s30, 0, s33
	v_subrev_u32_e32 v36, s9, v39
	s_or_b32 s6, s6, s31
	v_mov_b32_e32 v2, v1
	v_mov_b32_e32 v3, v1
	v_mov_b32_e32 v0, v1
	v_add_u32_e32 v170, 0x10000, v36
	s_add_u32 s6, s86, s6
	v_mov_b32_e32 v171, v1
	v_sub_u32_e32 v189, s33, v167
	v_or_b32_e32 v176, 0x200, v174
	v_mov_b32_e32 v177, s8
	v_mov_b32_e32 v175, s8
	s_addc_u32 s7, s87, s7
	v_mov_b32_e32 v190, 0
	v_mov_b32_e32 v191, 0xf149f2ca
	v_mov_b32_e32 v208, 0xf149f2ca
	s_waitcnt vmcnt(7)
	s_waitcnt vmcnt(6)
	s_waitcnt vmcnt(5)
	s_waitcnt vmcnt(4)
	s_waitcnt vmcnt(3)
	s_waitcnt vmcnt(2)
	s_waitcnt vmcnt(1)
	s_waitcnt vmcnt(0)
	ds_write_b128 v188, v[4:7] offset:16384
	ds_write_b128 v188, v[8:11] offset:17408
	ds_write_b128 v188, v[12:15] offset:18432
	ds_write_b128 v188, v[16:19] offset:19456
	ds_write_b128 v188, v[20:23] offset:20480
	ds_write_b128 v188, v[24:27] offset:21504
	ds_write_b128 v188, v[28:31] offset:22528
	ds_write_b128 v188, v[32:35] offset:23552
	v_mov_b32_e32 v14, v1
	v_mov_b32_e32 v15, v1
	v_mov_b32_e32 v4, v1
	v_mov_b32_e32 v5, v1
	v_mov_b32_e32 v6, v1
	v_mov_b32_e32 v7, v1
	v_mov_b32_e32 v8, v1
	v_mov_b32_e32 v9, v1
	v_mov_b32_e32 v10, v1
	v_mov_b32_e32 v11, v1
	v_mov_b32_e32 v12, v1
	v_mov_b32_e32 v13, v1
	v_mov_b64_e32 v[30:31], v[14:15]
	v_mov_b64_e32 v[62:63], v[14:15]
	v_mov_b64_e32 v[46:47], v[14:15]
	v_mov_b64_e32 v[78:79], v[14:15]
	v_mov_b64_e32 v[28:29], v[12:13]
	v_mov_b64_e32 v[26:27], v[10:11]
	v_mov_b64_e32 v[24:25], v[8:9]
	v_mov_b64_e32 v[22:23], v[6:7]
	v_mov_b64_e32 v[20:21], v[4:5]
	v_mov_b64_e32 v[18:19], v[2:3]
	v_mov_b64_e32 v[16:17], v[0:1]
	v_mov_b64_e32 v[60:61], v[12:13]
	v_mov_b64_e32 v[58:59], v[10:11]
	v_mov_b64_e32 v[56:57], v[8:9]
	v_mov_b64_e32 v[54:55], v[6:7]
	v_mov_b64_e32 v[52:53], v[4:5]
	v_mov_b64_e32 v[50:51], v[2:3]
	v_mov_b64_e32 v[48:49], v[0:1]
	v_mov_b64_e32 v[44:45], v[12:13]
	v_mov_b64_e32 v[42:43], v[10:11]
	v_mov_b64_e32 v[40:41], v[8:9]
	v_mov_b64_e32 v[38:39], v[6:7]
	v_mov_b64_e32 v[36:37], v[4:5]
	v_mov_b64_e32 v[34:35], v[2:3]
	v_mov_b64_e32 v[32:33], v[0:1]
	v_mov_b64_e32 v[76:77], v[12:13]
	v_mov_b64_e32 v[74:75], v[10:11]
	v_mov_b64_e32 v[72:73], v[8:9]
	v_mov_b64_e32 v[70:71], v[6:7]
	v_mov_b64_e32 v[68:69], v[4:5]
	v_mov_b64_e32 v[66:67], v[2:3]
	v_mov_b64_e32 v[64:65], v[0:1]
	v_mov_b32_e32 v15, 0

.LBB0_1429:
	v_mov_b32_e32 v4, v252
	s_waitcnt vmcnt(63) expcnt(7) lgkmcnt(15)
	v_readfirstlane_b32 s4, v4
	s_barrier
	s_load_dwordx2 s[2:3], s[0:1], 0x40
	s_ashr_i32 s10, s4, 6
	v_and_b32_e32 v173, 63, v4
	s_mul_i32 s6, s10, 0x101
	s_mul_i32 s5, s10, 0x410
	v_add_u32_e32 v2, s6, v173
	s_add_i32 s8, s5, 0
	v_ashrrev_i32_e32 v3, 31, v2
	v_or_b32_e32 v0, 0xffffffc0, v173
	v_lshl_add_u32 v5, v173, 2, s8
	s_waitcnt lgkmcnt(0)
	v_lshl_add_u64 v[2:3], v[2:3], 2, s[2:3]
	s_mov_b64 s[2:3], 0
	global_load_dword v243, v[2:3], off
	global_load_dword v248, v[2:3], off offset:256
	global_load_dword v249, v[2:3], off offset:512
	global_load_dword v250, v[2:3], off offset:768
	v_cmp_eq_u32_e32 vcc, 0xffffffc0, v0
	s_and_saveexec_b64 s[2:3], vcc
	global_load_dword v251, v[2:3], off offset:1024
	s_waitcnt vmcnt(0)
	v_mul_f32_e32 v251, 0x3fb8aa3b, v251
	ds_write_b32 v5, v251 offset:1024
	ds_write_b32 v5, v251 offset:1028
	ds_write_b32 v5, v251 offset:1032
	ds_write_b32 v5, v251 offset:1036
	s_or_b64 exec, exec, s[2:3]
	v_mul_f32_e32 v243, 0x3fb8aa3b, v243
	v_mul_f32_e32 v248, 0x3fb8aa3b, v248
	v_mul_f32_e32 v249, 0x3fb8aa3b, v249
	v_mul_f32_e32 v250, 0x3fb8aa3b, v250
	ds_write_b32 v5, v243
	ds_write_b32 v5, v248 offset:256
	ds_write_b32 v5, v249 offset:512
	ds_write_b32 v5, v250 offset:768
	s_add_i32 s11, s18, 0xffb9
	s_and_b32 s9, s11, 0xffff
	s_mul_i32 s2, s9, 0x8889
	s_lshr_b32 s2, s2, 22
	s_lshl_b32 s3, s2, 7
	s_mulk_i32 s2, 0x78
	s_sub_i32 s2, s11, s2
	s_add_i32 s2, s2, 8
	s_and_b32 s2, s2, 0xffff
	s_add_i32 s33, s3, s2
	s_lshr_b32 s2, s33, 7
	s_lshl_b32 s76, s2, 22
	s_lshl_b32 s2, s2, 3
	s_and_b32 s6, s4, 0xffffffc0
	s_add_i32 s2, s10, s2
	s_ashr_i32 s7, s6, 31
	s_ashr_i32 s3, s2, 31
	s_lshl_b64 s[2:3], s[2:3], 20
	s_lshl_b64 s[4:5], s[6:7], 1
	v_lshrrev_b32_e32 v5, 5, v173
	s_add_u32 s30, s95, s4
	v_and_b32_e32 v172, 31, v4
	s_addc_u32 s31, s22, s5
	v_lshlrev_b32_e32 v0, 4, v5
	v_lshl_add_u64 v[2:3], s[30:31], 0, v[0:1]
	v_lshl_or_b32 v0, s33, 6, v172
	v_lshlrev_b64 v[6:7], 10, v[0:1]
	v_or_b32_e32 v162, 32, v0
	v_mov_b32_e32 v163, v1
	v_lshl_add_u64 v[18:19], v[2:3], 0, v[6:7]
	v_lshlrev_b64 v[6:7], 10, v[162:163]
	s_waitcnt lgkmcnt(0)
	s_barrier
	v_lshl_add_u64 v[2:3], v[2:3], 0, v[6:7]
	global_load_dwordx4 v[6:9], v[18:19], off
	global_load_dwordx4 v[10:13], v[18:19], off offset:32
	global_load_dwordx4 v[14:17], v[18:19], off offset:64
	s_nop 0
	global_load_dwordx4 v[18:21], v[18:19], off offset:96
	s_nop 0
	global_load_dwordx4 v[22:25], v[2:3], off
	global_load_dwordx4 v[26:29], v[2:3], off offset:32
	global_load_dwordx4 v[30:33], v[2:3], off offset:64
	global_load_dwordx4 v[34:37], v[2:3], off offset:96
	s_mulk_i32 s10, 0x1bf0
	v_lshlrev_b32_e32 v38, 4, v173
	s_add_i32 s10, s8, s10
	v_and_b32_e32 v3, 32, v4
	v_add_u32_e32 v174, s10, v38
	s_lshl_b32 s10, s11, 16
	v_lshlrev_b32_e32 v2, 10, v172
	v_lshrrev_b32_e32 v3, 1, v3
	v_or3_b32 v2, s10, v2, v3
	s_lshl_b64 s[10:11], s[76:77], 1
	s_add_u32 s10, s10, s4
	v_mov_b32_e32 v3, v1
	s_addc_u32 s11, s11, s5
	v_lshl_add_u64 v[2:3], s[10:11], 0, v[2:3]
	s_mul_hi_u32 s10, s9, 0x2222223
	s_mul_hi_u32 s11, s10, 0x780000
	s_mul_i32 s30, s10, 0x780000
	v_subrev_co_u32_e32 v166, vcc, s30, v2
	v_mov_b32_e32 v2, s11
	s_lshl_b32 s9, s9, 13
	v_subb_co_u32_e32 v167, vcc, v3, v2, vcc
	s_add_u32 s2, s2, s9
	v_lshlrev_b32_e32 v2, 4, v172
	v_lshlrev_b32_e32 v3, 10, v5
	v_or3_b32 v2, v3, v2, s2
	s_addc_u32 s3, s3, 0
	v_or_b32_e32 v3, 0x200, v2
	s_mul_i32 s10, s10, 0xf0000
	v_mov_b32_e32 v4, s3
	v_subrev_co_u32_e32 v168, vcc, s10, v3
	v_lshlrev_b32_e32 v165, 2, v5
	s_nop 0
	v_subbrev_co_u32_e32 v169, vcc, 0, v4, vcc
	v_subrev_co_u32_e32 v170, vcc, s10, v2
	v_sub_u32_e32 v2, v172, v165
	s_nop 0
	v_subbrev_co_u32_e32 v171, vcc, 0, v4, vcc
	v_add_u32_e32 v177, 0x220, v2
	v_mov_b32_e32 v2, v1
	v_mov_b32_e32 v3, v1
	v_mov_b32_e32 v4, v1
	v_mov_b32_e32 v5, v1
	v_mov_b32_e32 v175, 0
	v_mov_b32_e32 v189, 0xf149f2ca
	s_mov_b32 s9, -1
	v_mov_b32_e32 v199, 0xf149f2ca
	v_mov_b32_e32 v176, 0
	v_readfirstlane_b32 s98, v252
	v_mbcnt_lo_u32_b32 v249, -1, 0
	v_mbcnt_hi_u32_b32 v249, -1, v249
	s_lshr_b32 s101, s98, 6
	s_lshl_b32 s98, s101, 13
	s_add_i32 s98, s98, 0x14000
	s_add_i32 s99, s98, 0x1c00
	s_mov_b32 s100, 0x1000
	s_cmp_eq_u32 s101, 7
	s_cselect_b32 s99, 0x3000, s99
	s_cselect_b32 s100, 0xfffe0400, s100
	v_and_b32_e32 v246, 31, v249
	v_lshrrev_b32_e32 v247, 5, v249
	v_bfe_u32 v248, v249, 1, 3
	v_lshl_add_u32 v250, v246, 7, s98
	v_xor_b32_e32 v241, v247, v248
	v_lshl_add_u32 v241, v241, 4, v250
	v_or_b32_e32 v242, 2, v247
	v_xor_b32_e32 v242, v242, v248
	v_lshl_add_u32 v242, v242, 4, v250
	v_or_b32_e32 v243, 4, v247
	v_xor_b32_e32 v243, v243, v248
	v_lshl_add_u32 v243, v243, 4, v250
	v_or_b32_e32 v244, 6, v247
	v_xor_b32_e32 v244, v244, v248
	v_lshl_add_u32 v244, v244, 4, v250
	v_mov_b32_e32 v245, 0x1000
	v_mov_b32_e32 v251, s100
	v_cmp_lt_u32_e32 vcc, 23, v246
	s_nop 1
	v_cndmask_b32_e32 v245, v245, v251, vcc
	v_add_u32_e32 v248, v244, v245
	v_add_u32_e32 v247, v243, v245
	v_add_u32_e32 v246, v242, v245
	v_add_u32_e32 v245, v241, v245
	v_lshrrev_b32_e32 v250, 3, v249
	v_lshlrev_b32_e32 v250, 10, v250
	v_and_b32_e32 v251, 7, v249
	v_lshrrev_b32_e32 v142, 4, v249
	v_xor_b32_e32 v251, v251, v142
	v_lshl_add_u32 v142, v251, 4, v250
	v_xor_b32_e32 v251, 4, v251
	v_lshl_add_u32 v250, v251, 4, v250
	v_add_u32_e32 v250, 0x2000, v250
	v_readfirstlane_b32 s100, v166
	v_readfirstlane_b32 s101, v167
	s_nop 0
	s_add_u32 s100, s100, s86
	s_addc_u32 s101, s101, s87
	s_add_u32 s100, s100, 0x85ee200
	s_addc_u32 s101, s101, 0
	v_mov_b32_e32 v143, 0
	v_mov_b32_e32 v251, 0
	v_lshl_add_u64 v[166:167], s[100:101], 0, v[142:143]
	v_lshl_add_u64 v[250:251], s[100:101], 0, v[250:251]
	s_mov_b64 s[100:101], 0x4000
	s_mov_b32 m0, s98
	s_nop 0
	global_load_lds_dwordx4 v[166:167], off
	s_add_i32 m0, s98, 0x400
	s_nop 0
	global_load_lds_dwordx4 v[250:251], off
	v_lshl_add_u64 v[142:143], v[166:167], 0, s[100:101]
	s_add_i32 m0, s98, 0x800
	s_nop 0
	global_load_lds_dwordx4 v[142:143], off
	v_lshl_add_u64 v[144:145], v[250:251], 0, s[100:101]
	s_add_i32 m0, s98, 0xc00
	s_nop 0
	global_load_lds_dwordx4 v[144:145], off
	v_lshl_add_u64 v[142:143], v[142:143], 0, s[100:101]
	s_add_i32 m0, s98, 0x1000
	s_nop 0
	global_load_lds_dwordx4 v[142:143], off
	v_lshl_add_u64 v[144:145], v[144:145], 0, s[100:101]
	s_add_i32 m0, s98, 0x1400
	s_nop 0
	global_load_lds_dwordx4 v[144:145], off
	v_lshl_add_u64 v[142:143], v[142:143], 0, s[100:101]
	s_add_i32 m0, s98, 0x1800
	s_nop 0
	global_load_lds_dwordx4 v[142:143], off
	v_lshl_add_u64 v[144:145], v[144:145], 0, s[100:101]
	s_mov_b32 m0, s99
	s_nop 0
	global_load_lds_dwordx4 v[144:145], off
	s_waitcnt vmcnt(7)
	s_waitcnt vmcnt(6)
	s_waitcnt vmcnt(5)
	s_waitcnt vmcnt(4)
	s_waitcnt vmcnt(3)
	s_waitcnt vmcnt(2)
	s_waitcnt vmcnt(1)
	s_waitcnt vmcnt(0)
	ds_write_b128 v174, v[6:9] offset:16384
	ds_write_b128 v174, v[10:13] offset:17408
	ds_write_b128 v174, v[14:17] offset:18432
	ds_write_b128 v174, v[18:21] offset:19456
	ds_write_b128 v174, v[22:25] offset:20480
	ds_write_b128 v174, v[26:29] offset:21504
	ds_write_b128 v174, v[30:33] offset:22528
	ds_write_b128 v174, v[34:37] offset:23552
	v_mov_b32_e32 v16, v1
	v_mov_b32_e32 v17, v1
	v_mov_b32_e32 v6, v1
	v_mov_b32_e32 v7, v1
	v_mov_b32_e32 v8, v1
	v_mov_b32_e32 v9, v1
	v_mov_b32_e32 v10, v1
	v_mov_b32_e32 v11, v1
	v_mov_b32_e32 v12, v1
	v_mov_b32_e32 v13, v1
	v_mov_b32_e32 v14, v1
	v_mov_b32_e32 v15, v1
	v_mov_b64_e32 v[48:49], v[16:17]
	v_mov_b64_e32 v[32:33], v[16:17]
	v_mov_b64_e32 v[64:65], v[16:17]
	v_mov_b64_e32 v[46:47], v[14:15]
	v_mov_b64_e32 v[44:45], v[12:13]
	v_mov_b64_e32 v[42:43], v[10:11]
	v_mov_b64_e32 v[40:41], v[8:9]
	v_mov_b64_e32 v[38:39], v[6:7]
	v_mov_b64_e32 v[36:37], v[4:5]
	v_mov_b64_e32 v[34:35], v[2:3]
	v_mov_b64_e32 v[30:31], v[14:15]
	v_mov_b64_e32 v[28:29], v[12:13]
	v_mov_b64_e32 v[26:27], v[10:11]
	v_mov_b64_e32 v[24:25], v[8:9]
	v_mov_b64_e32 v[22:23], v[6:7]
	v_mov_b64_e32 v[20:21], v[4:5]
	v_mov_b64_e32 v[18:19], v[2:3]
	v_mov_b64_e32 v[62:63], v[14:15]
	v_mov_b64_e32 v[60:61], v[12:13]
	v_mov_b64_e32 v[58:59], v[10:11]
	v_mov_b64_e32 v[56:57], v[8:9]
	v_mov_b64_e32 v[54:55], v[6:7]
	v_mov_b64_e32 v[52:53], v[4:5]
	v_mov_b64_e32 v[50:51], v[2:3]
	v_mov_b32_e32 v216, 0x3e38aa3b
	v_mov_b32_e32 v217, 0x3e38aa3b

.Lattn_nopf:
	v_lshl_add_u64 v[130:131], s[86:87], 0, v[170:171]
	v_add_co_u32_e32 v132, vcc, s88, v130
	s_nop 1
	v_addc_co_u32_e32 v133, vcc, 0, v131, vcc
	v_add_co_u32_e32 v130, vcc, s17, v130
	global_load_dwordx4 v[158:161], v[132:133], off offset:512
	global_load_dwordx4 v[154:157], v[132:133], off offset:1024
	global_load_dwordx4 v[150:153], v[132:133], off offset:2560
	global_load_dwordx4 v[146:149], v[132:133], off offset:3072
	v_addc_co_u32_e32 v131, vcc, 0, v131, vcc
	v_lshl_add_u64 v[132:133], s[86:87], 0, v[168:169]
	v_add_co_u32_e32 v132, vcc, 0xae6f000, v132
	s_nop 1
	v_addc_co_u32_e32 v133, vcc, 0, v133, vcc
	global_load_dwordx4 v[138:141], v[130:131], off offset:512
	global_load_dwordx4 v[134:137], v[130:131], off offset:2560
	global_load_dwordx4 v[142:145], v[132:133], off offset:512
	s_nop 0
	global_load_dwordx4 v[130:133], v[132:133], off offset:2560
	v_mov_b32_e32 v188, s8
	ds_read_b32 v190, v188 offset:1024
	s_cmp_lt_u32 s9, 6
	s_cbranch_scc0 .Lattn_far_p
	s_waitcnt vmcnt(8)
	v_subrev_u32_e32 v188, 64, v177
	v_xor_b32_e32 v198, 32, v179
	v_lshlrev_b32_e32 v198, 2, v198
	v_max3_f32 v231, v98, v99, v100
	v_max3_f32 v231, v231, v101, v102
	v_max3_f32 v231, v231, v103, v104
	v_max3_f32 v231, v231, v105, v106
	v_max3_f32 v231, v231, v107, v108
	v_max3_f32 v231, v231, v109, v110
	v_max3_f32 v231, v231, v111, v112
	v_max3_f32 v231, v231, v113, v114
	v_max3_f32 v231, v231, v115, v116
	v_max3_f32 v231, v231, v117, v118
	v_max3_f32 v231, v231, v119, v120
	v_max3_f32 v231, v231, v121, v122
	v_max3_f32 v231, v231, v123, v124
	v_max3_f32 v231, v231, v125, v126
	v_max3_f32 v231, v231, v127, v128
	v_max_f32_e32 v231, v231, v129
	s_waitcnt lgkmcnt(0)
	v_fma_f32 v231, v231, v216, v190
	ds_bpermute_b32 v233, v198, v231
	v_max3_f32 v234, v66, v67, v68
	v_max3_f32 v234, v234, v69, v70
	v_max3_f32 v234, v234, v71, v72
	v_max3_f32 v234, v234, v73, v74
	v_max3_f32 v234, v234, v75, v76
	v_max3_f32 v234, v234, v77, v78
	v_max3_f32 v234, v234, v79, v80
	v_max3_f32 v234, v234, v81, v82
	v_max3_f32 v234, v234, v83, v84
	v_max3_f32 v234, v234, v85, v86
	v_max3_f32 v234, v234, v87, v88
	v_max3_f32 v234, v234, v89, v90
	v_max3_f32 v234, v234, v91, v92
	v_max3_f32 v234, v234, v93, v94
	v_max3_f32 v234, v234, v95, v96
	v_max_f32_e32 v234, v234, v97
	v_fma_f32 v234, v234, v216, v190
	ds_bpermute_b32 v235, v198, v234
	s_waitcnt lgkmcnt(1)
	v_max3_f32 v236, v199, v231, v233
	v_sub_f32_e32 v226, v199, v236
	v_sub_f32_e32 v238, v190, v236
	v_sub_f32_e32 v239, v190, v236
	v_exp_f32_e32 v226, v226
	v_pk_fma_f32 v[98:99], v[98:99], v[216:217], v[238:239]
	v_pk_fma_f32 v[100:101], v[100:101], v[216:217], v[238:239]
	v_pk_fma_f32 v[102:103], v[102:103], v[216:217], v[238:239]
	v_pk_fma_f32 v[104:105], v[104:105], v[216:217], v[238:239]
	v_pk_fma_f32 v[106:107], v[106:107], v[216:217], v[238:239]
	v_pk_fma_f32 v[108:109], v[108:109], v[216:217], v[238:239]
	v_pk_fma_f32 v[110:111], v[110:111], v[216:217], v[238:239]
	v_pk_fma_f32 v[112:113], v[112:113], v[216:217], v[238:239]
	v_pk_fma_f32 v[114:115], v[114:115], v[216:217], v[238:239]
	v_pk_fma_f32 v[116:117], v[116:117], v[216:217], v[238:239]
	v_pk_fma_f32 v[118:119], v[118:119], v[216:217], v[238:239]
	v_pk_fma_f32 v[120:121], v[120:121], v[216:217], v[238:239]
	v_pk_fma_f32 v[122:123], v[122:123], v[216:217], v[238:239]
	v_pk_fma_f32 v[124:125], v[124:125], v[216:217], v[238:239]
	v_pk_fma_f32 v[126:127], v[126:127], v[216:217], v[238:239]
	v_pk_fma_f32 v[128:129], v[128:129], v[216:217], v[238:239]
	v_exp_f32_e32 v98, v98
	v_exp_f32_e32 v99, v99
	v_exp_f32_e32 v100, v100
	v_exp_f32_e32 v101, v101
	v_exp_f32_e32 v102, v102
	v_exp_f32_e32 v103, v103
	v_exp_f32_e32 v104, v104
	v_exp_f32_e32 v105, v105
	v_exp_f32_e32 v106, v106
	v_exp_f32_e32 v107, v107
	v_exp_f32_e32 v108, v108
	v_exp_f32_e32 v109, v109
	v_exp_f32_e32 v110, v110
	v_exp_f32_e32 v111, v111
	v_exp_f32_e32 v112, v112
	v_exp_f32_e32 v113, v113
	v_exp_f32_e32 v114, v114
	v_exp_f32_e32 v115, v115
	v_exp_f32_e32 v116, v116
	v_exp_f32_e32 v117, v117
	v_exp_f32_e32 v118, v118
	v_exp_f32_e32 v119, v119
	v_exp_f32_e32 v120, v120
	v_exp_f32_e32 v121, v121
	v_exp_f32_e32 v122, v122
	v_exp_f32_e32 v123, v123
	v_exp_f32_e32 v124, v124
	v_exp_f32_e32 v125, v125
	v_exp_f32_e32 v126, v126
	v_exp_f32_e32 v127, v127
	v_exp_f32_e32 v128, v128
	v_exp_f32_e32 v129, v129
	s_waitcnt lgkmcnt(0)
	v_max3_f32 v218, v189, v234, v235
	v_sub_f32_e32 v228, v189, v218
	v_sub_f32_e32 v202, v190, v218
	v_sub_f32_e32 v203, v190, v218
	v_exp_f32_e32 v228, v228
	v_pk_fma_f32 v[66:67], v[66:67], v[216:217], v[202:203]
	v_pk_fma_f32 v[68:69], v[68:69], v[216:217], v[202:203]
	v_pk_fma_f32 v[70:71], v[70:71], v[216:217], v[202:203]
	v_pk_fma_f32 v[72:73], v[72:73], v[216:217], v[202:203]
	v_pk_fma_f32 v[74:75], v[74:75], v[216:217], v[202:203]
	v_pk_fma_f32 v[76:77], v[76:77], v[216:217], v[202:203]
	v_pk_fma_f32 v[78:79], v[78:79], v[216:217], v[202:203]
	v_pk_fma_f32 v[80:81], v[80:81], v[216:217], v[202:203]
	v_pk_fma_f32 v[82:83], v[82:83], v[216:217], v[202:203]
	v_pk_fma_f32 v[84:85], v[84:85], v[216:217], v[202:203]
	v_pk_fma_f32 v[86:87], v[86:87], v[216:217], v[202:203]
	v_pk_fma_f32 v[88:89], v[88:89], v[216:217], v[202:203]
	v_pk_fma_f32 v[90:91], v[90:91], v[216:217], v[202:203]
	v_pk_fma_f32 v[92:93], v[92:93], v[216:217], v[202:203]
	v_pk_fma_f32 v[94:95], v[94:95], v[216:217], v[202:203]
	v_pk_fma_f32 v[96:97], v[96:97], v[216:217], v[202:203]
	v_exp_f32_e32 v66, v66
	v_exp_f32_e32 v67, v67
	v_exp_f32_e32 v68, v68
	v_exp_f32_e32 v69, v69
	v_exp_f32_e32 v70, v70
	v_exp_f32_e32 v71, v71
	v_exp_f32_e32 v72, v72
	v_exp_f32_e32 v73, v73
	v_exp_f32_e32 v74, v74
	v_exp_f32_e32 v75, v75
	v_exp_f32_e32 v76, v76
	v_exp_f32_e32 v77, v77
	v_exp_f32_e32 v78, v78
	v_exp_f32_e32 v79, v79
	v_exp_f32_e32 v80, v80
	v_exp_f32_e32 v81, v81
	v_exp_f32_e32 v82, v82
	v_exp_f32_e32 v83, v83
	v_exp_f32_e32 v84, v84
	v_exp_f32_e32 v85, v85
	v_exp_f32_e32 v86, v86
	v_exp_f32_e32 v87, v87
	v_exp_f32_e32 v88, v88
	v_exp_f32_e32 v89, v89
	v_exp_f32_e32 v90, v90
	v_exp_f32_e32 v91, v91
	v_exp_f32_e32 v92, v92
	v_exp_f32_e32 v93, v93
	v_exp_f32_e32 v94, v94
	v_exp_f32_e32 v95, v95
	v_exp_f32_e32 v96, v96
	v_exp_f32_e32 v97, v97
	v_pk_add_f32 v[212:213], v[98:99], v[100:101]
	v_pk_add_f32 v[214:215], v[102:103], v[104:105]
	v_pk_add_f32 v[212:213], v[212:213], v[106:107]
	v_pk_add_f32 v[214:215], v[214:215], v[108:109]
	v_pk_add_f32 v[212:213], v[212:213], v[110:111]
	v_pk_add_f32 v[214:215], v[214:215], v[112:113]
	v_pk_add_f32 v[212:213], v[212:213], v[114:115]
	v_pk_add_f32 v[214:215], v[214:215], v[116:117]
	v_pk_add_f32 v[212:213], v[212:213], v[118:119]
	v_pk_add_f32 v[214:215], v[214:215], v[120:121]
	v_pk_add_f32 v[212:213], v[212:213], v[122:123]
	v_pk_add_f32 v[214:215], v[214:215], v[124:125]
	v_pk_add_f32 v[212:213], v[212:213], v[126:127]
	v_pk_add_f32 v[214:215], v[214:215], v[128:129]
	v_pk_add_f32 v[212:213], v[212:213], v[214:215]
	v_add_f32_e32 v210, v212, v213
	ds_bpermute_b32 v211, v198, v210
	v_pk_add_f32 v[220:221], v[66:67], v[68:69]
	v_pk_add_f32 v[222:223], v[70:71], v[72:73]
	v_pk_add_f32 v[220:221], v[220:221], v[74:75]
	v_pk_add_f32 v[222:223], v[222:223], v[76:77]
	v_pk_add_f32 v[220:221], v[220:221], v[78:79]
	v_pk_add_f32 v[222:223], v[222:223], v[80:81]
	v_pk_add_f32 v[220:221], v[220:221], v[82:83]
	v_pk_add_f32 v[222:223], v[222:223], v[84:85]
	v_pk_add_f32 v[220:221], v[220:221], v[86:87]
	v_pk_add_f32 v[222:223], v[222:223], v[88:89]
	v_pk_add_f32 v[220:221], v[220:221], v[90:91]
	v_pk_add_f32 v[222:223], v[222:223], v[92:93]
	v_pk_add_f32 v[220:221], v[220:221], v[94:95]
	v_pk_add_f32 v[222:223], v[222:223], v[96:97]
	v_pk_add_f32 v[220:221], v[220:221], v[222:223]
	v_add_f32_e32 v224, v220, v221
	ds_bpermute_b32 v225, v198, v224
	v_cmp_neq_f32_e32 vcc, 1.0, v226
	s_cbranch_vccz .Lattn_near_p_sa
	v_mov_b32_e32 v227, v226
	v_pk_mul_f32 v[64:65], v[64:65], v[226:227]
	v_pk_mul_f32 v[62:63], v[62:63], v[226:227]
	v_pk_mul_f32 v[60:61], v[60:61], v[226:227]
	v_pk_mul_f32 v[58:59], v[58:59], v[226:227]
	v_pk_mul_f32 v[56:57], v[56:57], v[226:227]
	v_pk_mul_f32 v[54:55], v[54:55], v[226:227]
	v_pk_mul_f32 v[52:53], v[52:53], v[226:227]
	v_pk_mul_f32 v[50:51], v[50:51], v[226:227]
	v_pk_mul_f32 v[48:49], v[48:49], v[226:227]
	v_pk_mul_f32 v[46:47], v[46:47], v[226:227]
	v_pk_mul_f32 v[44:45], v[44:45], v[226:227]
	v_pk_mul_f32 v[42:43], v[42:43], v[226:227]
	v_pk_mul_f32 v[40:41], v[40:41], v[226:227]
	v_pk_mul_f32 v[38:39], v[38:39], v[226:227]
	v_pk_mul_f32 v[36:37], v[36:37], v[226:227]
	v_pk_mul_f32 v[34:35], v[34:35], v[226:227]

.Lattn_far_p:
	s_waitcnt vmcnt(8)
	v_subrev_u32_e32 v188, 64, v177
	v_xor_b32_e32 v198, 32, v179
	v_lshlrev_b32_e32 v198, 2, v198
	v_lshl_add_u32 v191, v177, 2, s8
	s_add_i32 s2, s8, 0x200
	v_add_u32_e32 v192, 0xfffffff4, v191
	v_min_i32_e32 v192, s2, v192
	ds_read2_b32 v[200:201], v192 offset0:131 offset1:130
	ds_read2_b32 v[202:203], v192 offset0:129 offset1:128
	v_add_u32_e32 v193, 0xffffffd4, v191
	v_min_i32_e32 v193, s2, v193
	ds_read2_b32 v[204:205], v193 offset0:131 offset1:130
	ds_read2_b32 v[206:207], v193 offset0:129 offset1:128
	v_add_u32_e32 v192, 0xffffffb4, v191
	v_min_i32_e32 v192, s2, v192
	ds_read2_b32 v[208:209], v192 offset0:131 offset1:130
	ds_read2_b32 v[210:211], v192 offset0:129 offset1:128
	v_add_u32_e32 v193, 0xffffff94, v191
	v_min_i32_e32 v193, s2, v193
	ds_read2_b32 v[212:213], v193 offset0:131 offset1:130
	ds_read2_b32 v[214:215], v193 offset0:129 offset1:128
	v_add_u32_e32 v192, 0xffffff74, v191
	v_min_i32_e32 v192, s2, v192
	ds_read2_b32 v[218:219], v192 offset0:131 offset1:130
	ds_read2_b32 v[220:221], v192 offset0:129 offset1:128
	v_add_u32_e32 v193, 0xffffff54, v191
	v_min_i32_e32 v193, s2, v193
	ds_read2_b32 v[222:223], v193 offset0:131 offset1:130
	ds_read2_b32 v[224:225], v193 offset0:129 offset1:128
	v_add_u32_e32 v192, 0xffffff34, v191
	v_min_i32_e32 v192, s2, v192
	ds_read2_b32 v[226:227], v192 offset0:131 offset1:130
	ds_read2_b32 v[228:229], v192 offset0:129 offset1:128
	s_waitcnt lgkmcnt(6)
	v_pk_fma_f32 v[66:67], v[66:67], v[216:217], v[200:201]
	v_pk_fma_f32 v[68:69], v[68:69], v[216:217], v[202:203]
	v_pk_fma_f32 v[70:71], v[70:71], v[216:217], v[204:205]
	v_pk_fma_f32 v[72:73], v[72:73], v[216:217], v[206:207]
	v_pk_fma_f32 v[74:75], v[74:75], v[216:217], v[208:209]
	v_pk_fma_f32 v[76:77], v[76:77], v[216:217], v[210:211]
	v_pk_fma_f32 v[78:79], v[78:79], v[216:217], v[212:213]
	v_pk_fma_f32 v[80:81], v[80:81], v[216:217], v[214:215]
	v_add_u32_e32 v193, 0xffffff14, v191
	v_min_i32_e32 v193, s2, v193
	ds_read2_b32 v[230:231], v193 offset0:131 offset1:130
	ds_read2_b32 v[232:233], v193 offset0:129 offset1:128
	v_add_u32_e32 v192, 0xfffffef4, v191
	v_min_i32_e32 v192, s2, v192
	ds_read2_b32 v[200:201], v192 offset0:131 offset1:130
	ds_read2_b32 v[202:203], v192 offset0:129 offset1:128
	v_add_u32_e32 v193, 0xfffffed4, v191
	v_min_i32_e32 v193, s2, v193
	ds_read2_b32 v[204:205], v193 offset0:131 offset1:130
	ds_read2_b32 v[206:207], v193 offset0:129 offset1:128
	v_add_u32_e32 v192, 0xfffffeb4, v191
	v_min_i32_e32 v192, s2, v192
	ds_read2_b32 v[208:209], v192 offset0:131 offset1:130
	ds_read2_b32 v[210:211], v192 offset0:129 offset1:128
	s_waitcnt lgkmcnt(6)
	v_pk_fma_f32 v[98:99], v[98:99], v[216:217], v[218:219]
	v_pk_fma_f32 v[100:101], v[100:101], v[216:217], v[220:221]
	v_pk_fma_f32 v[102:103], v[102:103], v[216:217], v[222:223]
	v_pk_fma_f32 v[104:105], v[104:105], v[216:217], v[224:225]
	v_pk_fma_f32 v[106:107], v[106:107], v[216:217], v[226:227]
	v_pk_fma_f32 v[108:109], v[108:109], v[216:217], v[228:229]
	v_pk_fma_f32 v[110:111], v[110:111], v[216:217], v[230:231]
	v_pk_fma_f32 v[112:113], v[112:113], v[216:217], v[232:233]
	v_pk_fma_f32 v[82:83], v[82:83], v[216:217], v[218:219]
	v_pk_fma_f32 v[84:85], v[84:85], v[216:217], v[220:221]
	v_pk_fma_f32 v[86:87], v[86:87], v[216:217], v[222:223]
	v_pk_fma_f32 v[88:89], v[88:89], v[216:217], v[224:225]
	v_pk_fma_f32 v[90:91], v[90:91], v[216:217], v[226:227]
	v_pk_fma_f32 v[92:93], v[92:93], v[216:217], v[228:229]
	v_pk_fma_f32 v[94:95], v[94:95], v[216:217], v[230:231]
	v_pk_fma_f32 v[96:97], v[96:97], v[216:217], v[232:233]
	v_add_u32_e32 v193, 0xfffffe94, v191
	v_min_i32_e32 v193, s2, v193
	ds_read2_b32 v[212:213], v193 offset0:131 offset1:130
	ds_read2_b32 v[214:215], v193 offset0:129 offset1:128
	s_waitcnt lgkmcnt(0)
	v_pk_fma_f32 v[114:115], v[114:115], v[216:217], v[200:201]
	v_pk_fma_f32 v[116:117], v[116:117], v[216:217], v[202:203]
	v_pk_fma_f32 v[118:119], v[118:119], v[216:217], v[204:205]
	v_pk_fma_f32 v[120:121], v[120:121], v[216:217], v[206:207]
	v_pk_fma_f32 v[122:123], v[122:123], v[216:217], v[208:209]
	v_pk_fma_f32 v[124:125], v[124:125], v[216:217], v[210:211]
	v_pk_fma_f32 v[126:127], v[126:127], v[216:217], v[212:213]
	v_pk_fma_f32 v[128:129], v[128:129], v[216:217], v[214:215]
	v_max3_f32 v231, v98, v99, v100
	v_max3_f32 v231, v231, v101, v102
	v_max3_f32 v231, v231, v103, v104
	v_max3_f32 v231, v231, v105, v106
	v_max3_f32 v231, v231, v107, v108
	v_max3_f32 v231, v231, v109, v110
	v_max3_f32 v231, v231, v111, v112
	v_max3_f32 v231, v231, v113, v114
	v_max3_f32 v231, v231, v115, v116
	v_max3_f32 v231, v231, v117, v118
	v_max3_f32 v231, v231, v119, v120
	v_max3_f32 v231, v231, v121, v122
	v_max3_f32 v231, v231, v123, v124
	v_max3_f32 v231, v231, v125, v126
	v_max3_f32 v231, v231, v127, v128
	v_max_f32_e32 v231, v231, v129
	ds_bpermute_b32 v233, v198, v231
	v_max3_f32 v234, v66, v67, v68
	v_max3_f32 v234, v234, v69, v70
	v_max3_f32 v234, v234, v71, v72
	v_max3_f32 v234, v234, v73, v74
	v_max3_f32 v234, v234, v75, v76
	v_max3_f32 v234, v234, v77, v78
	v_max3_f32 v234, v234, v79, v80
	v_max3_f32 v234, v234, v81, v82
	v_max3_f32 v234, v234, v83, v84
	v_max3_f32 v234, v234, v85, v86
	v_max3_f32 v234, v234, v87, v88
	v_max3_f32 v234, v234, v89, v90
	v_max3_f32 v234, v234, v91, v92
	v_max3_f32 v234, v234, v93, v94
	v_max3_f32 v234, v234, v95, v96
	v_max_f32_e32 v234, v234, v97
	ds_bpermute_b32 v235, v198, v234
	s_waitcnt lgkmcnt(1)
	v_max3_f32 v236, v199, v231, v233
	v_sub_f32_e32 v226, v199, v236
	v_sub_f32_e32 v238, 0, v236
	v_sub_f32_e32 v239, 0, v236
	v_exp_f32_e32 v226, v226
	v_pk_add_f32 v[98:99], v[98:99], v[238:239]
	v_pk_add_f32 v[100:101], v[100:101], v[238:239]
	v_pk_add_f32 v[102:103], v[102:103], v[238:239]
	v_pk_add_f32 v[104:105], v[104:105], v[238:239]
	v_pk_add_f32 v[106:107], v[106:107], v[238:239]
	v_pk_add_f32 v[108:109], v[108:109], v[238:239]
	v_pk_add_f32 v[110:111], v[110:111], v[238:239]
	v_pk_add_f32 v[112:113], v[112:113], v[238:239]
	v_pk_add_f32 v[114:115], v[114:115], v[238:239]
	v_pk_add_f32 v[116:117], v[116:117], v[238:239]
	v_pk_add_f32 v[118:119], v[118:119], v[238:239]
	v_pk_add_f32 v[120:121], v[120:121], v[238:239]
	v_pk_add_f32 v[122:123], v[122:123], v[238:239]
	v_pk_add_f32 v[124:125], v[124:125], v[238:239]
	v_pk_add_f32 v[126:127], v[126:127], v[238:239]
	v_pk_add_f32 v[128:129], v[128:129], v[238:239]
	v_exp_f32_e32 v98, v98
	v_exp_f32_e32 v99, v99
	v_exp_f32_e32 v100, v100
	v_exp_f32_e32 v101, v101
	v_exp_f32_e32 v102, v102
	v_exp_f32_e32 v103, v103
	v_exp_f32_e32 v104, v104
	v_exp_f32_e32 v105, v105
	v_exp_f32_e32 v106, v106
	v_exp_f32_e32 v107, v107
	v_exp_f32_e32 v108, v108
	v_exp_f32_e32 v109, v109
	v_exp_f32_e32 v110, v110
	v_exp_f32_e32 v111, v111
	v_exp_f32_e32 v112, v112
	v_exp_f32_e32 v113, v113
	v_exp_f32_e32 v114, v114
	v_exp_f32_e32 v115, v115
	v_exp_f32_e32 v116, v116
	v_exp_f32_e32 v117, v117
	v_exp_f32_e32 v118, v118
	v_exp_f32_e32 v119, v119
	v_exp_f32_e32 v120, v120
	v_exp_f32_e32 v121, v121
	v_exp_f32_e32 v122, v122
	v_exp_f32_e32 v123, v123
	v_exp_f32_e32 v124, v124
	v_exp_f32_e32 v125, v125
	v_exp_f32_e32 v126, v126
	v_exp_f32_e32 v127, v127
	v_exp_f32_e32 v128, v128
	v_exp_f32_e32 v129, v129
	s_waitcnt lgkmcnt(0)
	v_max3_f32 v218, v189, v234, v235
	v_sub_f32_e32 v228, v189, v218
	v_sub_f32_e32 v202, 0, v218
	v_sub_f32_e32 v203, 0, v218
	v_exp_f32_e32 v228, v228
	v_pk_add_f32 v[66:67], v[66:67], v[202:203]
	v_pk_add_f32 v[68:69], v[68:69], v[202:203]
	v_pk_add_f32 v[70:71], v[70:71], v[202:203]
	v_pk_add_f32 v[72:73], v[72:73], v[202:203]
	v_pk_add_f32 v[74:75], v[74:75], v[202:203]
	v_pk_add_f32 v[76:77], v[76:77], v[202:203]
	v_pk_add_f32 v[78:79], v[78:79], v[202:203]
	v_pk_add_f32 v[80:81], v[80:81], v[202:203]
	v_pk_add_f32 v[82:83], v[82:83], v[202:203]
	v_pk_add_f32 v[84:85], v[84:85], v[202:203]
	v_pk_add_f32 v[86:87], v[86:87], v[202:203]
	v_pk_add_f32 v[88:89], v[88:89], v[202:203]
	v_pk_add_f32 v[90:91], v[90:91], v[202:203]
	v_pk_add_f32 v[92:93], v[92:93], v[202:203]
	v_pk_add_f32 v[94:95], v[94:95], v[202:203]
	v_pk_add_f32 v[96:97], v[96:97], v[202:203]
	v_exp_f32_e32 v66, v66
	v_exp_f32_e32 v67, v67
	v_exp_f32_e32 v68, v68
	v_exp_f32_e32 v69, v69
	v_exp_f32_e32 v70, v70
	v_exp_f32_e32 v71, v71
	v_exp_f32_e32 v72, v72
	v_exp_f32_e32 v73, v73
	v_exp_f32_e32 v74, v74
	v_exp_f32_e32 v75, v75
	v_exp_f32_e32 v76, v76
	v_exp_f32_e32 v77, v77
	v_exp_f32_e32 v78, v78
	v_exp_f32_e32 v79, v79
	v_exp_f32_e32 v80, v80
	v_exp_f32_e32 v81, v81
	v_exp_f32_e32 v82, v82
	v_exp_f32_e32 v83, v83
	v_exp_f32_e32 v84, v84
	v_exp_f32_e32 v85, v85
	v_exp_f32_e32 v86, v86
	v_exp_f32_e32 v87, v87
	v_exp_f32_e32 v88, v88
	v_exp_f32_e32 v89, v89
	v_exp_f32_e32 v90, v90
	v_exp_f32_e32 v91, v91
	v_exp_f32_e32 v92, v92
	v_exp_f32_e32 v93, v93
	v_exp_f32_e32 v94, v94
	v_exp_f32_e32 v95, v95
	v_exp_f32_e32 v96, v96
	v_exp_f32_e32 v97, v97
	v_pk_add_f32 v[212:213], v[98:99], v[100:101]
	v_pk_add_f32 v[214:215], v[102:103], v[104:105]
	v_pk_add_f32 v[212:213], v[212:213], v[106:107]
	v_pk_add_f32 v[214:215], v[214:215], v[108:109]
	v_pk_add_f32 v[212:213], v[212:213], v[110:111]
	v_pk_add_f32 v[214:215], v[214:215], v[112:113]
	v_pk_add_f32 v[212:213], v[212:213], v[114:115]
	v_pk_add_f32 v[214:215], v[214:215], v[116:117]
	v_pk_add_f32 v[212:213], v[212:213], v[118:119]
	v_pk_add_f32 v[214:215], v[214:215], v[120:121]
	v_pk_add_f32 v[212:213], v[212:213], v[122:123]
	v_pk_add_f32 v[214:215], v[214:215], v[124:125]
	v_pk_add_f32 v[212:213], v[212:213], v[126:127]
	v_pk_add_f32 v[214:215], v[214:215], v[128:129]
	v_pk_add_f32 v[212:213], v[212:213], v[214:215]
	v_add_f32_e32 v210, v212, v213
	ds_bpermute_b32 v211, v198, v210
	v_pk_add_f32 v[220:221], v[66:67], v[68:69]
	v_pk_add_f32 v[222:223], v[70:71], v[72:73]
	v_pk_add_f32 v[220:221], v[220:221], v[74:75]
	v_pk_add_f32 v[222:223], v[222:223], v[76:77]
	v_pk_add_f32 v[220:221], v[220:221], v[78:79]
	v_pk_add_f32 v[222:223], v[222:223], v[80:81]
	v_pk_add_f32 v[220:221], v[220:221], v[82:83]
	v_pk_add_f32 v[222:223], v[222:223], v[84:85]
	v_pk_add_f32 v[220:221], v[220:221], v[86:87]
	v_pk_add_f32 v[222:223], v[222:223], v[88:89]
	v_pk_add_f32 v[220:221], v[220:221], v[90:91]
	v_pk_add_f32 v[222:223], v[222:223], v[92:93]
	v_pk_add_f32 v[220:221], v[220:221], v[94:95]
	v_pk_add_f32 v[222:223], v[222:223], v[96:97]
	v_pk_add_f32 v[220:221], v[220:221], v[222:223]
	v_add_f32_e32 v224, v220, v221
	ds_bpermute_b32 v225, v198, v224
	v_cmp_neq_f32_e32 vcc, 1.0, v226
	s_cbranch_vccz .Lattn_far_p_sa
	v_mov_b32_e32 v227, v226
	v_pk_mul_f32 v[64:65], v[64:65], v[226:227]
	v_pk_mul_f32 v[62:63], v[62:63], v[226:227]
	v_pk_mul_f32 v[60:61], v[60:61], v[226:227]
	v_pk_mul_f32 v[58:59], v[58:59], v[226:227]
	v_pk_mul_f32 v[56:57], v[56:57], v[226:227]
	v_pk_mul_f32 v[54:55], v[54:55], v[226:227]
	v_pk_mul_f32 v[52:53], v[52:53], v[226:227]
	v_pk_mul_f32 v[50:51], v[50:51], v[226:227]
	v_pk_mul_f32 v[48:49], v[48:49], v[226:227]
	v_pk_mul_f32 v[46:47], v[46:47], v[226:227]
	v_pk_mul_f32 v[44:45], v[44:45], v[226:227]
	v_pk_mul_f32 v[42:43], v[42:43], v[226:227]
	v_pk_mul_f32 v[40:41], v[40:41], v[226:227]
	v_pk_mul_f32 v[38:39], v[38:39], v[226:227]
	v_pk_mul_f32 v[36:37], v[36:37], v[226:227]
	v_pk_mul_f32 v[34:35], v[34:35], v[226:227]

.Lattn_far_p_sb:
	v_cvt_pk_bf16_f32 v98, v98, v99
	v_cvt_pk_bf16_f32 v99, v100, v101
	v_cvt_pk_bf16_f32 v100, v102, v103
	v_cvt_pk_bf16_f32 v101, v104, v105
	v_cvt_pk_bf16_f32 v66, v66, v67
	v_cvt_pk_bf16_f32 v67, v68, v69
	v_cvt_pk_bf16_f32 v68, v70, v71
	v_cvt_pk_bf16_f32 v69, v72, v73
	s_waitcnt vmcnt(7)
	v_mfma_f32_32x32x16_bf16 v[50:65], v[158:161], v[98:101], v[50:65]
	v_cvt_pk_bf16_f32 v102, v106, v107
	v_cvt_pk_bf16_f32 v103, v108, v109
	v_cvt_pk_bf16_f32 v104, v110, v111
	v_cvt_pk_bf16_f32 v105, v112, v113
	v_mfma_f32_32x32x16_bf16 v[18:33], v[158:161], v[66:69], v[18:33]
	v_cvt_pk_bf16_f32 v70, v74, v75
	v_cvt_pk_bf16_f32 v71, v76, v77
	v_cvt_pk_bf16_f32 v72, v78, v79
	v_cvt_pk_bf16_f32 v73, v80, v81
	s_waitcnt vmcnt(6)
	v_mfma_f32_32x32x16_bf16 v[34:49], v[154:157], v[98:101], v[34:49]
	v_mfma_f32_32x32x16_bf16 v[2:17], v[154:157], v[66:69], v[2:17]
	v_cvt_pk_bf16_f32 v106, v114, v115
	v_cvt_pk_bf16_f32 v107, v116, v117
	v_cvt_pk_bf16_f32 v108, v118, v119
	v_cvt_pk_bf16_f32 v109, v120, v121
	v_cvt_pk_bf16_f32 v74, v82, v83
	v_cvt_pk_bf16_f32 v75, v84, v85
	v_cvt_pk_bf16_f32 v76, v86, v87
	v_cvt_pk_bf16_f32 v77, v88, v89
	s_waitcnt vmcnt(5)
	v_mfma_f32_32x32x16_bf16 v[50:65], v[150:153], v[102:105], v[50:65]
	v_mfma_f32_32x32x16_bf16 v[18:33], v[150:153], v[70:73], v[18:33]
	s_waitcnt vmcnt(4)
	v_mfma_f32_32x32x16_bf16 v[34:49], v[146:149], v[102:105], v[34:49]
	v_mfma_f32_32x32x16_bf16 v[2:17], v[146:149], v[70:73], v[2:17]
	v_cvt_pk_bf16_f32 v110, v122, v123
	v_cvt_pk_bf16_f32 v111, v124, v125
	v_cvt_pk_bf16_f32 v112, v126, v127
	v_cvt_pk_bf16_f32 v113, v128, v129
	v_cvt_pk_bf16_f32 v78, v90, v91
	v_cvt_pk_bf16_f32 v79, v92, v93
	v_cvt_pk_bf16_f32 v80, v94, v95
	v_cvt_pk_bf16_f32 v81, v96, v97
	s_waitcnt vmcnt(3)
	v_mfma_f32_32x32x16_bf16 v[50:65], v[138:141], v[106:109], v[50:65]
	v_mfma_f32_32x32x16_bf16 v[18:33], v[138:141], v[74:77], v[18:33]
	s_waitcnt vmcnt(1)
	v_mfma_f32_32x32x16_bf16 v[34:49], v[142:145], v[106:109], v[34:49]
	v_mfma_f32_32x32x16_bf16 v[2:17], v[142:145], v[74:77], v[2:17]
	v_mfma_f32_32x32x16_bf16 v[50:65], v[134:137], v[110:113], v[50:65]
	v_mfma_f32_32x32x16_bf16 v[18:33], v[134:137], v[78:81], v[18:33]
	s_waitcnt lgkmcnt(0)
	v_add_f32_e32 v210, v210, v211
	v_add_f32_e32 v224, v224, v225
	v_fma_f32 v176, v176, v226, v210
	v_fma_f32 v175, v175, v228, v224
	v_lshl_add_u64 v[168:169], v[168:169], 0, s[84:85]
	v_lshl_add_u64 v[170:171], v[170:171], 0, s[84:85]
	s_waitcnt vmcnt(0)
	v_mfma_f32_32x32x16_bf16 v[34:49], v[130:133], v[110:113], v[34:49]
	v_mfma_f32_32x32x16_bf16 v[2:17], v[130:133], v[78:81], v[2:17]
	v_mov_b32_e32 v177, v188
	v_mov_b32_e32 v189, v218
	v_mov_b32_e32 v199, v236
	s_cmp_gt_u32 s9, 7
	s_cbranch_scc0 .LBB0_1432
	v_mov_b32_e32 v66, v176
	v_mov_b32_e32 v86, v175
	v_mov_b32_e32 v99, v198
